# v63 + MLA softmax section: exps of the first two groups as one block of 16, plain VALU of both groups after it (fewer trans/plain transitions; MFMA order unchanged)
# baseline (speedup 1.0000x reference)
.LBB0_1482:
	v_exp_f32_e32 v66, v66
	v_exp_f32_e32 v67, v67
	v_exp_f32_e32 v68, v68
	v_exp_f32_e32 v69, v69
	v_exp_f32_e32 v70, v70
	v_exp_f32_e32 v71, v71
	v_exp_f32_e32 v72, v72
	v_exp_f32_e32 v73, v73
	v_exp_f32_e32 v74, v74
	v_exp_f32_e32 v75, v75
	v_exp_f32_e32 v76, v76
	v_exp_f32_e32 v77, v77
	v_exp_f32_e32 v78, v78
	v_exp_f32_e32 v79, v79
	v_exp_f32_e32 v80, v80
	v_exp_f32_e32 v81, v81
	v_pk_add_f32 v[154:155], v[66:67], v[68:69]
	v_pk_add_f32 v[156:157], v[70:71], v[72:73]
	v_pk_add_f32 v[158:159], v[154:155], v[156:157]
	v_cvt_pk_bf16_f32 v66, v66, v67
	v_cvt_pk_bf16_f32 v67, v68, v69
	v_cvt_pk_bf16_f32 v68, v70, v71
	v_cvt_pk_bf16_f32 v69, v72, v73
	v_pk_add_f32 v[154:155], v[74:75], v[76:77]
	v_pk_add_f32 v[156:157], v[78:79], v[80:81]
	v_mfma_f32_32x32x16_bf16 v[18:33], v[66:69], v[150:153], v[18:33]
	v_pk_add_f32 v[160:161], v[154:155], v[156:157]
	s_waitcnt lgkmcnt(6)
	v_mfma_f32_32x32x16_bf16 v[34:49], v[66:69], v[134:137], v[34:49]
	v_cvt_pk_bf16_f32 v70, v74, v75
	v_cvt_pk_bf16_f32 v71, v76, v77
	v_cvt_pk_bf16_f32 v72, v78, v79
	v_cvt_pk_bf16_f32 v73, v80, v81
	v_exp_f32_e32 v82, v82
	v_exp_f32_e32 v83, v83
	v_mfma_f32_32x32x16_bf16 v[18:33], v[70:73], v[146:149], v[18:33]
	v_exp_f32_e32 v84, v84
	v_exp_f32_e32 v85, v85
	v_exp_f32_e32 v86, v86
	s_waitcnt lgkmcnt(4)
	v_mfma_f32_32x32x16_bf16 v[34:49], v[70:73], v[130:133], v[34:49]
	v_exp_f32_e32 v87, v87
	v_exp_f32_e32 v88, v88
	v_exp_f32_e32 v89, v89
	v_pk_add_f32 v[154:155], v[82:83], v[84:85]
	v_pk_add_f32 v[156:157], v[86:87], v[88:89]
	v_pk_add_f32 v[162:163], v[154:155], v[156:157]
	v_cvt_pk_bf16_f32 v74, v82, v83
	v_cvt_pk_bf16_f32 v75, v84, v85
	v_cvt_pk_bf16_f32 v76, v86, v87
	v_cvt_pk_bf16_f32 v77, v88, v89
	v_exp_f32_e32 v90, v90
	v_exp_f32_e32 v91, v91
	v_mfma_f32_32x32x16_bf16 v[18:33], v[74:77], v[142:145], v[18:33]
	v_exp_f32_e32 v92, v92
	v_exp_f32_e32 v93, v93
	v_exp_f32_e32 v94, v94
	s_waitcnt lgkmcnt(2)
	v_mfma_f32_32x32x16_bf16 v[34:49], v[74:77], v[126:129], v[34:49]
	v_exp_f32_e32 v95, v95
	v_exp_f32_e32 v96, v96
	v_exp_f32_e32 v97, v97
	v_pk_add_f32 v[154:155], v[90:91], v[92:93]
	v_pk_add_f32 v[156:157], v[94:95], v[96:97]
	v_pk_add_f32 v[164:165], v[154:155], v[156:157]
	v_cvt_pk_bf16_f32 v78, v90, v91
	v_cvt_pk_bf16_f32 v79, v92, v93
	v_cvt_pk_bf16_f32 v80, v94, v95
	v_cvt_pk_bf16_f32 v81, v96, v97
	v_pk_add_f32 v[158:159], v[158:159], v[160:161]
	s_add_u32 s24, s24, 0x10000
	s_addc_u32 s25, s25, 0
	v_mfma_f32_32x32x16_bf16 v[18:33], v[78:81], v[138:141], v[18:33]
	v_pk_add_f32 v[162:163], v[162:163], v[164:165]
	s_add_u32 s22, s22, 0x1000
	s_addc_u32 s23, s23, 0
	s_waitcnt lgkmcnt(0)
	v_mfma_f32_32x32x16_bf16 v[34:49], v[78:81], v[122:125], v[34:49]
	v_pk_add_f32 v[158:159], v[158:159], v[162:163]
	v_add_f32_e32 v158, v158, v159
	v_add_u32_e32 v66, s56, v182
	v_add_f32_e32 v173, v173, v158
	v_add_u32_e32 v67, v66, v184
	v_add_u32_e32 v66, v66, v189
	s_cmp_eq_u32 s24, 0x200000
	s_waitcnt vmcnt(0) lgkmcnt(0)
	s_barrier
	ds_read_b128 v[82:85], v67
	s_cbranch_scc1 .LBB0_1484
	s_mov_b32 s49, s57
	s_mul_i32 s52, s49, 0x3000
	s_branch .Lmla2_reads2
